# end-of-layer barrier keeps the cross-XCD rendezvous but skips the L2 writeback in local mode (only XCD-private dirty lines remain there)
# baseline (speedup 1.0000x reference)
; __device__ __forceinline__ unsigned xb_add(unsigned* p, unsigned v) { return __hip_atomic_fetch_add(p, v, __ATOMIC_RELAXED, __HIP_MEMORY_SCOPE_AGENT); }
; __device__ __forceinline__ void xcd_barrier(const XcdBarrier& b) {
;     ...
;         if (old + 1u == (gen + 1u) * nloc) {
;             __builtin_amdgcn_fence(__ATOMIC_RELEASE, "agent");
;             asm volatile("s_waitcnt vmcnt(0)" ::: "memory");
;             const unsigned og = xb_add(&bar[XB_TOP], 1u);
;             const unsigned tg = og / nx;
;             if (og + 1u == (tg + 1u) * nx) xb_add(&bar[XB_TOPGEN], 1u);
.Lxb_nowb_5:
	s_waitcnt lgkmcnt(0)
	s_waitcnt vmcnt(0)
	v_mbcnt_lo_u32_b32 v1, s4, 0
	v_mbcnt_hi_u32_b32 v1, s5, v1
	v_cmp_eq_u32_e32 vcc, 0, v1
	s_and_saveexec_b64 s[6:7], vcc
	s_cbranch_execz .LBB0_1161
	s_bcnt1_i32_b64 s4, s[4:5]
	v_mov_b32_e32 v2, s4
	v_readlane_b32 s4, v253, 42
	v_readlane_b32 s5, v253, 43
	s_nop 4
	global_atomic_add v2, v181, v2, s[4:5] sc0
